# attncsel + HGRN: removed the full lgkmcnt(0) drains before the three MFMA groups per chunk (the compiler's counted lgkmcnt waits per MFMA remain)
# speedup vs baseline: 1.0031x; 1.0031x over previous
; __device__ __forceinline__ void hgrn_phase(const Params& p, int e, char* lds) {
;     ...
;         { const int j0 = 16 * wq + 4 * fq_;
;           { const int tcol = 16 * ttA + fr; u32x2 w; w.x = cvtpk_c(j0 + 0 <= tcol ? acc0[0] : 0.f, j0 + 1 <= tcol ? acc0[1] : 0.f); w.y = cvtpk_c(j0 + 2 <= tcol ? acc0[2] : 0.f, j0 + 3 <= tcol ? acc0[3] : 0.f);
;             *(u32x2*)(PP + tcol * PJ + j0 * 2) = w; }
;           { const int tcol = 16 * (ttA + 1) + fr; u32x2 w; w.x = cvtpk_c(j0 + 0 <= tcol ? acc1[0] : 0.f, j0 + 1 <= tcol ? acc1[1] : 0.f); w.y = cvtpk_c(j0 + 2 <= tcol ? acc1[2] : 0.f, j0 + 3 <= tcol ? acc1[3] : 0.f);
;             *(u32x2*)(PP + tcol * PJ + j0 * 2) = w; } } }
;       { const f32x4 d4 = *(const f32x4*)(DD + 16 * wq + 4 * fq_); char* STn = ST + (pb ^ 1) * (128 * PK);
;         const bf16x8 a0 = ldfrag(KS, 16 * wq + fr, PJ, fq_ * 8), a1 = ldfrag(KS, 16 * wq + fr, PJ, 32 + fq_ * 8);
;         bf16x8 v0[4], v1[4];
; #pragma unroll
;         for (int n = 0; n < 4; ++n) { v0[n] = ldfrag(VT, 16 * (vt0 + n) + fr, PJ, fq_ * 8); v1[n] = ldfrag(VT, 16 * (vt0 + n) + fr, PJ, 32 + fq_ * 8); }
;         HWAIT();
; #pragma unroll
;         for (int n = 0; n < 4; ++n) { Sacc[n] = Sacc[n] * d4;
;           Sacc[n] = __builtin_amdgcn_mfma_f32_16x16x32_bf16(a0, v0[n], Sacc[n], 0, 0, 0);
;           Sacc[n] = __builtin_amdgcn_mfma_f32_16x16x32_bf16(a1, v1[n], Sacc[n], 0, 0, 0); }
; #pragma unroll
;         for (int n = 0; n < 4; ++n) { u32x2 w; w.x = cvtpk_c(Sacc[n][0], Sacc[n][1]); w.y = cvtpk_c(Sacc[n][2], Sacc[n][3]);
;           *(u32x2*)(STn + (16 * (vt0 + n) + fr) * PK + (16 * wq + 4 * fq_) * 2) = w; } }
;       LBAR();
;       { bf16x8 pf[2], vf[4][2];
; #pragma unroll
;         for (int ks = 0; ks < 2; ++ks) { pf[ks] = ldfrag(PP, 16 * wq + fr, PJ, ks * 32 + fq_ * 8);
; #pragma unroll
;           for (int n = 0; n < 4; ++n) vf[n][ks] = ldfrag(VT, 16 * (vt0 + n) + fr, PJ, ks * 32 + fq_ * 8); }
;         HWAIT();
; #pragma unroll
;         for (int ks = 0; ks < 2; ++ks)
; #pragma unroll
;           for (int n = 0; n < 4; ++n) oacc[n] = __builtin_amdgcn_mfma_f32_16x16x32_bf16(pf[ks], vf[n][ks], oacc[n], 0, 0, 0);
; #pragma unroll
;         for (int n = 0; n < 4; ++n) { const int oo = obase + osb * (64 * c + 16 * wq + 4 * fq_) + (16 * (vt0 + n) + fr) * 2;
; #pragma unroll
.LBB0_212:
	s_or_b64 exec, exec, s[26:27]
	s_waitcnt lgkmcnt(3)
	v_mfma_f32_16x16x32_bf16 v[40:43], v[16:19], v[40:43], v[80:83]
	s_nop 1
	v_cvt_pk_bf16_f32 v28, v28, s0
	v_cndmask_b32_e64 v28, v28, 0, s[48:49]
	s_lshl_b32 s5, s36, 26
	s_waitcnt lgkmcnt(2)
	v_mfma_f32_16x16x32_bf16 v[36:39], v[16:19], v[36:39], v[72:75]
	s_and_b32 s5, s5, 0xc000000
	v_or_b32_e32 v44, s5, v118
	v_lshl_or_b32 v44, s4, 8, v44
	s_waitcnt lgkmcnt(1)
	v_mfma_f32_16x16x32_bf16 v[32:35], v[16:19], v[32:35], v[60:63]
	v_lshl_add_u32 v44, s35, 10, v44
	v_or_b32_e32 v76, v44, v123
	v_or_b32_e32 v77, v44, v124
	s_waitcnt lgkmcnt(0)
	v_mfma_f32_16x16x32_bf16 v[16:19], v[16:19], v[20:23], v[56:59]
	v_cvt_pk_bf16_f32 v20, v29, s0
	v_cvt_pk_bf16_f32 v21, v30, s0
	v_cvt_pk_bf16_f32 v22, v31, s0
	v_cndmask_b32_e64 v20, 0, v20, s[50:51]
	v_cndmask_b32_e64 v21, v21, 0, s[52:53]
	v_cndmask_b32_e64 v22, v22, 0, s[54:55]
	v_perm_b32 v20, v20, v28, s7
	v_perm_b32 v21, v22, v21, s7
	ds_write_b64 v84, v[20:21] offset:55296
	v_cvt_pk_bf16_f32 v20, v24, s0
	v_cvt_pk_bf16_f32 v21, v25, s0
	v_cndmask_b32_e64 v20, v20, 0, s[56:57]
	v_cndmask_b32_e64 v21, 0, v21, s[58:59]
	v_perm_b32 v20, v21, v20, s7
	v_cvt_pk_bf16_f32 v21, v26, s0
	v_cvt_pk_bf16_f32 v22, v27, s0
	v_cndmask_b32_e64 v21, v21, 0, s[60:61]
	v_cndmask_b32_e64 v22, v22, 0, s[62:63]
	v_perm_b32 v21, v22, v21, s7
	ds_write_b64 v157, v[20:21] offset:55296
	v_or_b32_e32 v78, v44, v125
	v_or_b32_e32 v79, v44, v126
	ds_read_b128 v[20:23], v116
	ds_read_b128 v[24:27], v156 offset:27648
	ds_read_b128 v[28:31], v156 offset:27712
	ds_read_b128 v[44:47], v158 offset:36864
	ds_read_b128 v[48:51], v158 offset:36928
	ds_read_b128 v[52:55], v159 offset:36864
	ds_read_b128 v[56:59], v159 offset:36928
	ds_read_b128 v[60:63], v160 offset:36864
	ds_read_b128 v[64:67], v160 offset:36928
	ds_read_b128 v[68:71], v161 offset:36864
	ds_read_b128 v[72:75], v161 offset:36928
	s_waitcnt lgkmcnt(10)
	v_pk_mul_f32 v[10:11], v[10:11], v[22:23]
	v_pk_mul_f32 v[8:9], v[8:9], v[20:21]
	v_pk_mul_f32 v[14:15], v[14:15], v[22:23]
	v_pk_mul_f32 v[12:13], v[12:13], v[20:21]
	s_waitcnt lgkmcnt(7)
	v_mfma_f32_16x16x32_bf16 v[8:11], v[24:27], v[44:47], v[8:11]
	v_mul_f32_e64 v6, v6, v22
	v_mul_f32_e64 v7, v7, v23
	v_pk_mul_f32 v[4:5], v[4:5], v[20:21]
	v_pk_mul_f32 v[2:3], v[2:3], v[22:23]
	v_pk_mul_f32 v[0:1], v[0:1], v[20:21]
	s_waitcnt lgkmcnt(5)
	v_mfma_f32_16x16x32_bf16 v[12:15], v[24:27], v[52:55], v[12:15]
	s_waitcnt lgkmcnt(3)
	v_mfma_f32_16x16x32_bf16 v[4:7], v[24:27], v[60:63], v[4:7]
	s_waitcnt lgkmcnt(1)
	v_mfma_f32_16x16x32_bf16 v[0:3], v[24:27], v[68:71], v[0:3]
	v_mfma_f32_16x16x32_bf16 v[8:11], v[28:31], v[48:51], v[8:11]
	v_mfma_f32_16x16x32_bf16 v[12:15], v[28:31], v[56:59], v[12:15]
	v_mfma_f32_16x16x32_bf16 v[4:7], v[28:31], v[64:67], v[4:7]
	s_nop 5
	v_cvt_pk_bf16_f32 v8, v8, v9
	v_cvt_pk_bf16_f32 v9, v10, v11
	v_add_u32_e32 v10, v117, v101
	s_waitcnt lgkmcnt(0)
	v_mfma_f32_16x16x32_bf16 v[0:3], v[28:31], v[72:75], v[0:3]
	ds_write_b64 v10, v[8:9] offset:64512
	v_cvt_pk_bf16_f32 v8, v12, v13
	v_cvt_pk_bf16_f32 v9, v14, v15
	v_add_u32_e32 v10, v117, v119
	v_cvt_pk_bf16_f32 v4, v4, v5
	v_cvt_pk_bf16_f32 v5, v6, v7
	v_add_u32_e32 v6, v117, v120
	s_nop 0
	v_cvt_pk_bf16_f32 v0, v0, v1
	v_cvt_pk_bf16_f32 v1, v2, v3
	v_add_u32_e32 v2, v117, v121
	ds_write_b64 v10, v[8:9] offset:64512
	ds_write_b64 v6, v[4:5] offset:64512
	ds_write_b64 v2, v[0:1] offset:64512
	s_waitcnt lgkmcnt(0)
	s_barrier
	ds_read_b128 v[0:3], v156 offset:55296
	ds_read_b128 v[4:7], v156 offset:55360
	ds_read_b128 v[8:11], v85 offset:36864
	ds_read_b128 v[12:15], v85 offset:36928
	ds_read_b128 v[20:23], v86 offset:36864
	ds_read_b128 v[24:27], v86 offset:36928
	ds_read_b128 v[28:31], v87 offset:36864
	ds_read_b128 v[44:47], v87 offset:36928
	ds_read_b128 v[48:51], v88 offset:36864
	ds_read_b128 v[52:55], v88 offset:36928
	s_waitcnt lgkmcnt(7)
	v_mfma_f32_16x16x32_bf16 v[8:11], v[0:3], v[8:11], v[40:43]
	v_readlane_b32 s4, v254, 28
	s_add_i32 s39, s39, s4
	v_readlane_b32 s4, v254, 30
	s_waitcnt lgkmcnt(5)
	v_mfma_f32_16x16x32_bf16 v[20:23], v[0:3], v[20:23], v[36:39]
	s_add_i32 s36, s36, s9
	s_add_i32 s2, s2, s4
	s_cmpk_gt_i32 s36, 0xff
	s_waitcnt lgkmcnt(3)
	v_mfma_f32_16x16x32_bf16 v[28:31], v[0:3], v[28:31], v[32:35]
	s_waitcnt lgkmcnt(1)
	v_mfma_f32_16x16x32_bf16 v[0:3], v[0:3], v[48:51], v[16:19]
	v_mfma_f32_16x16x32_bf16 v[8:11], v[4:7], v[12:15], v[8:11]
	v_mfma_f32_16x16x32_bf16 v[12:15], v[4:7], v[24:27], v[20:23]
	v_mfma_f32_16x16x32_bf16 v[16:19], v[4:7], v[44:47], v[28:31]
	s_waitcnt lgkmcnt(0)
	v_mfma_f32_16x16x32_bf16 v[0:3], v[4:7], v[52:55], v[0:3]
	v_mul_lo_u32 v5, s34, v128
	s_nop 2
	v_cvt_pk_bf16_f32 v4, v8, s0
	v_add_u32_e32 v6, v76, v5
	global_store_short v6, v4, s[96:97]
	v_add_u32_e32 v6, s34, v5
	v_cvt_pk_bf16_f32 v4, v9, s0
	v_add_u32_e32 v7, v76, v6
	global_store_short v7, v4, s[96:97]
	v_add_u32_e32 v7, s34, v6
	v_cvt_pk_bf16_f32 v4, v10, s0
	v_add_u32_e32 v8, v76, v7
	global_store_short v8, v4, s[96:97]
	v_add_u32_e32 v8, s34, v7
	v_cvt_pk_bf16_f32 v4, v11, s0
	v_add_u32_e32 v9, v76, v8
	global_store_short v9, v4, s[96:97]
	v_cvt_pk_bf16_f32 v4, v12, s0
	v_add_u32_e32 v9, v77, v5
	global_store_short v9, v4, s[96:97]
	v_cvt_pk_bf16_f32 v4, v13, s0
	v_add_u32_e32 v9, v77, v6
	global_store_short v9, v4, s[96:97]
	v_cvt_pk_bf16_f32 v4, v14, s0
	v_add_u32_e32 v9, v77, v7
	global_store_short v9, v4, s[96:97]
	v_cvt_pk_bf16_f32 v4, v15, s0
	v_add_u32_e32 v9, v77, v8
	global_store_short v9, v4, s[96:97]
	v_cvt_pk_bf16_f32 v4, v16, s0
	v_add_u32_e32 v9, v78, v5
	global_store_short v9, v4, s[96:97]
	v_cvt_pk_bf16_f32 v4, v17, s0
	v_add_u32_e32 v9, v78, v6
	global_store_short v9, v4, s[96:97]
	v_cvt_pk_bf16_f32 v4, v18, s0
	v_add_u32_e32 v9, v78, v7
	global_store_short v9, v4, s[96:97]
	v_cvt_pk_bf16_f32 v4, v19, s0
	v_add_u32_e32 v9, v78, v8
	global_store_short v9, v4, s[96:97]
	v_cvt_pk_bf16_f32 v0, v0, s0
	v_add_u32_e32 v4, v79, v5
	global_store_short v4, v0, s[96:97]
	v_cvt_pk_bf16_f32 v0, v1, s0
	v_add_u32_e32 v1, v79, v6
	global_store_short v1, v0, s[96:97]
	v_cvt_pk_bf16_f32 v0, v2, s0
	v_add_u32_e32 v1, v79, v7
	global_store_short v1, v0, s[96:97]
	v_cvt_pk_bf16_f32 v0, v3, s0
	v_add_u32_e32 v1, v79, v8
	global_store_short v1, v0, s[96:97]
	s_barrier
	s_cbranch_scc1 .LBB0_242

; __device__ __forceinline__ void hgrn_phase(const Params& p, int e, char* lds) {
;     ...
;         { const int j0 = 16 * wq + 4 * fq_;
;           { const int tcol = 16 * ttA + fr; u32x2 w; w.x = cvtpk_c(j0 + 0 <= tcol ? acc0[0] : 0.f, j0 + 1 <= tcol ? acc0[1] : 0.f); w.y = cvtpk_c(j0 + 2 <= tcol ? acc0[2] : 0.f, j0 + 3 <= tcol ? acc0[3] : 0.f);
;             *(u32x2*)(PP + tcol * PJ + j0 * 2) = w; }
;           { const int tcol = 16 * (ttA + 1) + fr; u32x2 w; w.x = cvtpk_c(j0 + 0 <= tcol ? acc1[0] : 0.f, j0 + 1 <= tcol ? acc1[1] : 0.f); w.y = cvtpk_c(j0 + 2 <= tcol ? acc1[2] : 0.f, j0 + 3 <= tcol ? acc1[3] : 0.f);
;             *(u32x2*)(PP + tcol * PJ + j0 * 2) = w; } } }
;       { const f32x4 d4 = *(const f32x4*)(DD + 16 * wq + 4 * fq_); char* STn = ST + (pb ^ 1) * (128 * PK);
;         const bf16x8 a0 = ldfrag(KS, 16 * wq + fr, PJ, fq_ * 8), a1 = ldfrag(KS, 16 * wq + fr, PJ, 32 + fq_ * 8);
;         bf16x8 v0[4], v1[4];
; #pragma unroll
;         for (int n = 0; n < 4; ++n) { v0[n] = ldfrag(VT, 16 * (vt0 + n) + fr, PJ, fq_ * 8); v1[n] = ldfrag(VT, 16 * (vt0 + n) + fr, PJ, 32 + fq_ * 8); }
;         HWAIT();
; #pragma unroll
;         for (int n = 0; n < 4; ++n) { Sacc[n] = Sacc[n] * d4;
;           Sacc[n] = __builtin_amdgcn_mfma_f32_16x16x32_bf16(a0, v0[n], Sacc[n], 0, 0, 0);
;           Sacc[n] = __builtin_amdgcn_mfma_f32_16x16x32_bf16(a1, v1[n], Sacc[n], 0, 0, 0); }
; #pragma unroll
;         for (int n = 0; n < 4; ++n) { u32x2 w; w.x = cvtpk_c(Sacc[n][0], Sacc[n][1]); w.y = cvtpk_c(Sacc[n][2], Sacc[n][3]);
;           *(u32x2*)(STn + (16 * (vt0 + n) + fr) * PK + (16 * wq + 4 * fq_) * 2) = w; } }
;       LBAR();
;       { bf16x8 pf[2], vf[4][2];
; #pragma unroll
;         for (int ks = 0; ks < 2; ++ks) { pf[ks] = ldfrag(PP, 16 * wq + fr, PJ, ks * 32 + fq_ * 8);
; #pragma unroll
;           for (int n = 0; n < 4; ++n) vf[n][ks] = ldfrag(VT, 16 * (vt0 + n) + fr, PJ, ks * 32 + fq_ * 8); }
;         HWAIT();
; #pragma unroll
;         for (int ks = 0; ks < 2; ++ks)
; #pragma unroll
;           for (int n = 0; n < 4; ++n) oacc[n] = __builtin_amdgcn_mfma_f32_16x16x32_bf16(pf[ks], vf[n][ks], oacc[n], 0, 0, 0);
; #pragma unroll
;         for (int n = 0; n < 4; ++n) { const int oo = obase + osb * (64 * c + 16 * wq + 4 * fq_) + (16 * (vt0 + n) + fr) * 2;
; #pragma unroll
.LBB0_221:
	s_or_b64 exec, exec, s[26:27]
	s_nop 3
	v_cvt_pk_bf16_f32 v56, v60, s0
	v_mfma_f32_16x16x32_bf16 v[48:51], v[32:35], v[48:51], v[84:87]
	v_cvt_pk_bf16_f32 v57, v61, s0
	v_cndmask_b32_e64 v56, v56, 0, s[48:49]
	v_cndmask_b32_e64 v57, 0, v57, s[50:51]
	v_mfma_f32_16x16x32_bf16 v[44:47], v[32:35], v[44:47], v[80:83]
	v_perm_b32 v56, v57, v56, s7
	v_cvt_pk_bf16_f32 v57, v62, s0
	v_cvt_pk_bf16_f32 v58, v63, s0
	v_mfma_f32_16x16x32_bf16 v[40:43], v[32:35], v[40:43], v[76:79]
	v_cndmask_b32_e64 v57, v57, 0, s[52:53]
	v_cndmask_b32_e64 v58, v58, 0, s[54:55]
	v_perm_b32 v57, v58, v57, s7
	s_waitcnt lgkmcnt(0)
	v_mfma_f32_16x16x32_bf16 v[32:35], v[32:35], v[36:39], v[72:75]
	v_cvt_pk_bf16_f32 v36, v52, s0
	v_cvt_pk_bf16_f32 v37, v53, s0
	v_cndmask_b32_e64 v36, v36, 0, s[56:57]
	v_cndmask_b32_e64 v37, 0, v37, s[58:59]
	v_perm_b32 v36, v37, v36, s7
	v_cvt_pk_bf16_f32 v37, v54, s0
	v_cvt_pk_bf16_f32 v38, v55, s0
	v_cndmask_b32_e64 v37, v37, 0, s[60:61]
	v_cndmask_b32_e64 v38, v38, 0, s[62:63]
	v_add_u32_e32 v84, v111, v115
	v_perm_b32 v37, v38, v37, s7
	ds_write_b64 v84, v[56:57] offset:55296
	ds_write_b64 v157, v[36:37] offset:55296
	ds_read_b128 v[36:39], v116
	ds_read_b128 v[52:55], v156 offset:27648
	ds_read_b128 v[56:59], v156 offset:27712
	ds_read_b128 v[60:63], v158 offset:36864
	ds_read_b128 v[64:67], v158 offset:36928
	ds_read_b128 v[68:71], v159 offset:36864
	ds_read_b128 v[72:75], v159 offset:36928
	ds_read_b128 v[76:79], v160 offset:36864
	ds_read_b128 v[80:83], v160 offset:36928
	ds_read_b128 v[86:89], v161 offset:36864
	ds_read_b128 v[90:93], v161 offset:36928
	s_add_i32 vcc_lo, vcc_lo, 1
	s_xor_b32 s5, s14, 1
	s_waitcnt lgkmcnt(10)
	v_pk_mul_f32 v[10:11], v[10:11], v[38:39]
	v_pk_mul_f32 v[8:9], v[8:9], v[36:37]
	v_pk_mul_f32 v[14:15], v[14:15], v[38:39]
	v_pk_mul_f32 v[12:13], v[12:13], v[36:37]
	s_waitcnt lgkmcnt(7)
	v_mfma_f32_16x16x32_bf16 v[8:11], v[52:55], v[60:63], v[8:11]
	v_mul_f32_e64 v6, v6, v38
	v_mul_f32_e64 v7, v7, v39
	v_pk_mul_f32 v[4:5], v[4:5], v[36:37]
	v_pk_mul_f32 v[2:3], v[2:3], v[38:39]
	s_waitcnt lgkmcnt(5)
	v_mfma_f32_16x16x32_bf16 v[12:15], v[52:55], v[68:71], v[12:15]
	v_mul_f32_e64 v0, v0, v36
	v_mul_f32_e64 v1, v1, v37
	s_mulk_i32 s5, 0x4800
	v_add_u32_e32 v38, s5, v117
	s_waitcnt lgkmcnt(3)
	v_mfma_f32_16x16x32_bf16 v[4:7], v[52:55], v[76:79], v[4:7]
	v_add_u32_e32 v39, v38, v101
	v_add_u32_e32 v85, v122, v101
	s_waitcnt lgkmcnt(1)
	v_mfma_f32_16x16x32_bf16 v[0:3], v[52:55], v[86:89], v[0:3]
	v_add_u32_e32 v86, v122, v119
	v_add_u32_e32 v87, v122, v120
	v_add_u32_e32 v88, v122, v121
	v_mfma_f32_16x16x32_bf16 v[8:11], v[56:59], v[64:67], v[8:11]
	v_mfma_f32_16x16x32_bf16 v[12:15], v[56:59], v[72:75], v[12:15]
	v_mfma_f32_16x16x32_bf16 v[4:7], v[56:59], v[80:83], v[4:7]
	s_nop 5
	v_cvt_pk_bf16_f32 v36, v8, v9
	v_cvt_pk_bf16_f32 v37, v10, v11
	ds_write_b64 v39, v[36:37] offset:64512
	s_waitcnt lgkmcnt(1)
	v_mfma_f32_16x16x32_bf16 v[0:3], v[56:59], v[90:93], v[0:3]
	v_cvt_pk_bf16_f32 v36, v12, v13
	v_cvt_pk_bf16_f32 v37, v14, v15
	v_add_u32_e32 v39, v38, v119
	ds_write_b64 v39, v[36:37] offset:64512
	v_cvt_pk_bf16_f32 v36, v4, v5
	v_cvt_pk_bf16_f32 v37, v6, v7
	v_add_u32_e32 v39, v38, v120
	ds_write_b64 v39, v[36:37] offset:64512
	v_cvt_pk_bf16_f32 v36, v0, v1
	v_cvt_pk_bf16_f32 v37, v2, v3
	v_add_u32_e32 v38, v38, v121
	ds_write_b64 v38, v[36:37] offset:64512
	s_waitcnt lgkmcnt(0)
	s_barrier
	ds_read_b128 v[36:39], v156 offset:55296
	ds_read_b128 v[52:55], v156 offset:55360
	ds_read_b128 v[56:59], v85 offset:36864
	ds_read_b128 v[60:63], v85 offset:36928
	ds_read_b128 v[64:67], v86 offset:36864
	ds_read_b128 v[68:71], v86 offset:36928
	ds_read_b128 v[72:75], v87 offset:36864
	ds_read_b128 v[76:79], v87 offset:36928
	ds_read_b128 v[80:83], v88 offset:36864
	ds_read_b128 v[90:93], v88 offset:36928
	s_waitcnt lgkmcnt(7)
	v_mfma_f32_16x16x32_bf16 v[48:51], v[36:39], v[56:59], v[48:51]
	v_add_u32_e32 v56, vcc_hi, v167
	v_add_u32_e32 v57, vcc_hi, v164
	v_add_u32_e32 v58, vcc_hi, v165
	s_waitcnt lgkmcnt(5)
	v_mfma_f32_16x16x32_bf16 v[44:47], v[36:39], v[64:67], v[44:47]
	v_add_u32_e32 v164, s12, v164
	v_add_u32_e32 v165, s12, v165
	v_add_u32_e32 v167, s12, v167
	v_mfma_f32_16x16x32_bf16 v[48:51], v[52:55], v[60:63], v[48:51]
	v_add_u32_e32 v168, s10, v168
	v_add_u32_e32 v169, s10, v169
	v_add_u32_e32 v170, s10, v170
	s_waitcnt lgkmcnt(3)
	v_mfma_f32_16x16x32_bf16 v[40:43], v[36:39], v[72:75], v[40:43]
	s_cmp_eq_u32 vcc_lo, 63
	s_nop 1
	v_cvt_pk_bf16_f32 v48, v48, s0
	v_cvt_pk_bf16_f32 v49, v49, s0
	v_mfma_f32_16x16x32_bf16 v[44:47], v[52:55], v[68:71], v[44:47]
	v_cvt_pk_bf16_f32 v50, v50, s0
	global_store_short v56, v48, s[96:97]
	global_store_short v57, v49, s[96:97]
	v_cvt_pk_bf16_f32 v48, v51, s0
	v_add_u32_e32 v49, vcc_hi, v166
	s_waitcnt lgkmcnt(1)
	v_mfma_f32_16x16x32_bf16 v[32:35], v[36:39], v[80:83], v[32:35]
	global_store_short v58, v50, s[96:97]
	global_store_short v49, v48, s[96:97]
	v_cvt_pk_bf16_f32 v44, v44, s0
	v_mfma_f32_16x16x32_bf16 v[36:39], v[52:55], v[76:79], v[40:43]
	v_add_u32_e32 v48, 32, v56
	global_store_short v48, v44, s[96:97]
	v_cvt_pk_bf16_f32 v44, v45, s0
	v_add_u32_e32 v45, 32, v57
	global_store_short v45, v44, s[96:97]
	v_cvt_pk_bf16_f32 v44, v46, s0
	v_add_u32_e32 v45, 32, v58
	v_cvt_pk_bf16_f32 v40, v47, s0
	v_add_u32_e32 v41, 32, v49
	global_store_short v45, v44, s[96:97]
	s_waitcnt lgkmcnt(0)
	v_mfma_f32_16x16x32_bf16 v[32:35], v[52:55], v[90:93], v[32:35]
	global_store_short v41, v40, s[96:97]
	v_cvt_pk_bf16_f32 v36, v36, s0
	v_add_u32_e32 v40, 64, v56
	global_store_short v40, v36, s[96:97]
	v_cvt_pk_bf16_f32 v36, v37, s0
	v_add_u32_e32 v37, 64, v57
	global_store_short v37, v36, s[96:97]
	v_cvt_pk_bf16_f32 v36, v38, s0
	v_add_u32_e32 v37, 64, v58
	global_store_short v37, v36, s[96:97]
	v_cvt_pk_bf16_f32 v36, v39, s0
	v_add_u32_e32 v37, 64, v49
	global_store_short v37, v36, s[96:97]
	v_cvt_pk_bf16_f32 v32, v32, s0
	v_add_u32_e32 v36, 0x60, v56
	global_store_short v36, v32, s[96:97]
	v_cvt_pk_bf16_f32 v32, v33, s0
	v_add_u32_e32 v33, 0x60, v57
	global_store_short v33, v32, s[96:97]
	v_cvt_pk_bf16_f32 v32, v34, s0
	v_add_u32_e32 v33, 0x60, v58
	global_store_short v33, v32, s[96:97]
	v_cvt_pk_bf16_f32 v32, v35, s0
	v_add_u32_e32 v33, 0x60, v49
	v_add_u32_e32 v166, s12, v166
	v_add_u32_e32 v172, s10, v172
	global_store_short v33, v32, s[96:97]
	s_cbranch_scc1 .LBB0_232
; __device__ __forceinline__ void hgrn_phase(const Params& p, int e, char* lds) {
;     ...
;       *(u32x4*)(RQ + lr * PK + lc8 * 2) = gq; *(u32x4*)(RZ + lr * PK + lc8 * 2) = gz;
;       *(u32x4*)(RV + vr * PV + vc8 * 2) = gv0; *(u32x4*)(RV + (vr + 32) * PV + vc8 * 2) = gv1;
;       LBAR();
;       float qf[8], kk[8], cl[8]; float run = 0.f;
; #pragma unroll
;       for (int i = 0; i < 8; ++i) { const int t = 8 * rq + i; const float z = bf2f(*(const unsigned short*)(RZ + t * PK + k * 2)); qf[i] = bf2f(*(const unsigned short*)(RQ + t * PK + k * 2));
;         const float sg = __builtin_amdgcn_rcpf(1.0f + __builtin_amdgcn_exp2f(-L2E * z)); const float f = lbk + (1.0f - lbk) * sg;
;         run += __builtin_amdgcn_logf(f); cl[i] = run; kk[i] = 1.0f - f; }
;       TOT[rq * 64 + k] = run;
;       unsigned short rvv[16];
; #pragma unroll
;       for (int i = 0; i < 16; ++i) rvv[i] = *(const unsigned short*)(RV + (16 * jg + i) * PV + vv * 2);
;       u32x4 vpa, vpb;
;       vpa.x = rvv[0] | ((unsigned)rvv[1] << 16); vpa.y = rvv[2] | ((unsigned)rvv[3] << 16); vpa.z = rvv[4] | ((unsigned)rvv[5] << 16); vpa.w = rvv[6] | ((unsigned)rvv[7] << 16);
;       vpb.x = rvv[8] | ((unsigned)rvv[9] << 16); vpb.y = rvv[10] | ((unsigned)rvv[11] << 16); vpb.z = rvv[12] | ((unsigned)rvv[13] << 16); vpb.w = rvv[14] | ((unsigned)rvv[15] << 16);
;       LBAR();
;       { float tt[8];
; #pragma unroll
;         for (int r8 = 0; r8 < 8; ++r8) tt[r8] = TOT[r8 * 64 + k];
;         const float mid = (tt[0] + tt[1]) + (tt[2] + tt[3]), last = mid + ((tt[4] + tt[5]) + (tt[6] + tt[7]));
;         float off = 0.f;
; #pragma unroll
;         for (int r8 = 0; r8 < 7; ++r8) off += (r8 < rq) ? tt[r8] : 0.f;
;         const float el = __builtin_amdgcn_exp2f(last), em = __builtin_amdgcn_exp2f(fminf(-mid, 120.f)), emi = __builtin_amdgcn_exp2f(mid);
;         if (rq == 0) DD[k] = el;
;         unsigned ksw[4];
; #pragma unroll
;         for (int i = 0; i < 8; ++i) { const float cc = off + cl[i];
;           const float e1 = __builtin_amdgcn_exp2f(cc), inv1 = __builtin_amdgcn_exp2f(fminf(-cc, 120.f));
;           const float ea = fminf(e1 * em, 3.6e16f), eb = fminf(inv1 * emi, 3.6e16f), es = fminf(inv1 * el, 1.0f);
;           const int t = 8 * rq + i;
;           const unsigned w0 = cvtpk(qf[i] * e1, qf[i] * ea), w1 = cvtpk(kk[i] * eb, kk[i] * es);
.LBB0_222:
	s_waitcnt vmcnt(16)
	ds_write_b128 v143, v[16:19]
	ds_write_b128 v143, v[20:23] offset:9216
	ds_write_b128 v152, v[24:27] offset:18432
	ds_write_b128 v152, v[28:31] offset:27136
	s_waitcnt lgkmcnt(0)
	s_barrier
	ds_read_u16 v16, v100 offset:9216
	ds_read_u16 v17, v100 offset:9360
	ds_read_u16 v18, v100 offset:9504
	ds_read_u16 v19, v100 offset:9648
	ds_read_u16 v20, v100 offset:9792
	ds_read_u16 v21, v100 offset:9936
	ds_read_u16 v22, v100 offset:10080
	ds_read_u16 v23, v100 offset:10224
	s_waitcnt lgkmcnt(6)
	v_lshlrev_b32_e32 v17, 16, v17
	v_mul_f32_e32 v17, 0xbfb8aa3b, v17
	v_exp_f32_e32 v17, v17
	v_lshlrev_b32_e32 v16, 16, v16
	v_mul_f32_e32 v16, 0xbfb8aa3b, v16
	s_waitcnt lgkmcnt(5)
	v_lshlrev_b32_e32 v18, 16, v18
	v_exp_f32_e32 v16, v16
	v_add_f32_e32 v17, 1.0, v17
	v_mul_f32_e32 v18, 0xbfb8aa3b, v18
	v_rcp_f32_e32 v17, v17
	v_exp_f32_e32 v18, v18
	v_add_f32_e32 v16, 1.0, v16
	v_rcp_f32_e32 v16, v16
	v_fma_f32 v33, v163, v17, v162
	v_add_f32_e32 v17, 1.0, v18
	s_waitcnt lgkmcnt(4)
	v_lshlrev_b32_e32 v18, 16, v19
	v_mul_f32_e32 v18, 0xbfb8aa3b, v18
	v_rcp_f32_e32 v17, v17
	v_exp_f32_e32 v18, v18
	v_fma_f32 v32, v163, v16, v162
	v_log_f32_e32 v16, v32
	v_log_f32_e32 v19, v33
	v_fma_f32 v34, v163, v17, v162
	v_add_f32_e32 v18, 1.0, v18
	v_log_f32_e32 v17, v34
	v_rcp_f32_e32 v18, v18
	v_add_f32_e32 v31, 0, v16
	v_add_f32_e32 v30, v31, v19
	v_add_f32_e32 v29, v30, v17
	v_fma_f32 v37, v163, v18, v162
	s_waitcnt lgkmcnt(3)
	v_lshlrev_b32_e32 v17, 16, v20
	s_waitcnt lgkmcnt(2)
	v_lshlrev_b32_e32 v18, 16, v21
	v_mul_f32_e32 v17, 0xbfb8aa3b, v17
	v_mul_f32_e32 v18, 0xbfb8aa3b, v18
	v_log_f32_e32 v16, v37
	v_exp_f32_e32 v17, v17
	v_exp_f32_e32 v18, v18
	ds_read_u16 v57, v100
	ds_read_u16 v55, v100 offset:144
	ds_read_u16 v54, v100 offset:288
	ds_read_u16 v52, v100 offset:432
	ds_read_u16 v50, v100 offset:576
	ds_read_u16 v49, v100 offset:720
	ds_read_u16 v47, v100 offset:864
	ds_read_u16 v45, v100 offset:1008
	v_add_f32_e32 v27, v29, v16
	v_add_f32_e32 v16, 1.0, v17
	v_add_f32_e32 v17, 1.0, v18
	s_waitcnt lgkmcnt(9)
	v_lshlrev_b32_e32 v18, 16, v22
	v_mul_f32_e32 v18, 0xbfb8aa3b, v18
	v_rcp_f32_e32 v17, v17
	v_exp_f32_e32 v18, v18
	v_rcp_f32_e32 v16, v16
	v_fma_f32 v39, v163, v17, v162
	v_add_f32_e32 v17, 1.0, v18
	s_waitcnt lgkmcnt(8)
	v_lshlrev_b32_e32 v18, 16, v23
	v_mul_f32_e32 v18, 0xbfb8aa3b, v18
	v_exp_f32_e32 v18, v18
	v_rcp_f32_e32 v17, v17
	v_fma_f32 v38, v163, v16, v162
	v_log_f32_e32 v16, v38
	v_add_f32_e32 v18, 1.0, v18
	v_rcp_f32_e32 v18, v18
	v_log_f32_e32 v19, v39
	v_fma_f32 v40, v163, v17, v162
	v_log_f32_e32 v17, v40
	v_fma_f32 v41, v163, v18, v162
	v_add_f32_e32 v28, v27, v16
	v_log_f32_e32 v16, v41
	v_add_f32_e32 v26, v28, v19
	v_add_f32_e32 v25, v26, v17
	v_add_f32_e32 v24, v25, v16
	ds_write_b32 v107, v24
	ds_read_u16 v35, v153 offset:18432
	ds_read_u16 v36, v153 offset:18704
	ds_read_u16 v43, v153 offset:18976
	ds_read_u16 v44, v153 offset:19248
	ds_read_u16 v46, v153 offset:19520
	ds_read_u16 v48, v153 offset:19792
	ds_read_u16 v51, v153 offset:20064
	ds_read_u16 v53, v153 offset:20336
	ds_read_u16 v56, v153 offset:20608
	ds_read_u16 v58, v153 offset:20880
	ds_read_u16 v59, v153 offset:21152
	ds_read_u16 v60, v153 offset:21424
	ds_read_u16 v61, v153 offset:21696
	ds_read_u16 v62, v153 offset:21968
	ds_read_u16 v63, v153 offset:22240
	ds_read_u16 v64, v153 offset:22512
	s_waitcnt lgkmcnt(0)
	s_barrier
	ds_read2st64_b32 v[20:21], v108 offset0:2 offset1:3
	ds_read2st64_b32 v[18:19], v108 offset0:4 offset1:5
	ds_read2st64_b32 v[16:17], v108 offset0:6 offset1:7
	ds_read2st64_b32 v[22:23], v108 offset1:1
	s_waitcnt lgkmcnt(3)
	v_add_f32_e32 v42, v20, v21
	s_waitcnt lgkmcnt(2)
	v_add_f32_e32 v65, v18, v19
	s_waitcnt lgkmcnt(1)
	v_add_f32_e32 v17, v16, v17
	v_add_f32_e32 v17, v65, v17
	s_waitcnt lgkmcnt(0)
	v_add_f32_e32 v65, v22, v23
	v_add_f32_e32 v42, v65, v42
	v_add_f32_e32 v17, v42, v17
	v_exp_f32_e32 v17, v17
	s_and_saveexec_b64 s[26:27], s[42:43]
	ds_write_b32 v109, v17
	s_or_b64 exec, exec, s[26:27]
	v_add_f32_e32 v22, 0, v22
	v_cndmask_b32_e64 v22, 0, v22, s[64:65]
	v_cndmask_b32_e64 v23, 0, v23, s[66:67]
	v_add_f32_e32 v22, v22, v23
	v_cndmask_b32_e64 v20, 0, v20, s[68:69]
	v_add_f32_e32 v20, v22, v20
	v_cndmask_b32_e64 v21, 0, v21, s[70:71]
	v_add_f32_e32 v20, v20, v21
	v_cndmask_b32_e64 v18, 0, v18, s[72:73]
	v_add_f32_e32 v18, v20, v18
	v_cndmask_b32_e64 v19, 0, v19, s[74:75]
	v_add_f32_e32 v18, v18, v19
	v_cndmask_b32_e64 v16, 0, v16, s[76:77]
	v_add_f32_e32 v16, v18, v16
	v_max_f32_e64 v18, -v42, -v42
	v_min_f32_e32 v18, 0x42f00000, v18
	v_exp_f32_e32 v21, v18
	v_add_f32_e32 v18, v31, v16
	v_exp_f32_e32 v19, v18
	v_min_f32_e64 v18, -v18, s33
	v_exp_f32_e32 v22, v42
	v_exp_f32_e32 v18, v18
	v_lshlrev_b32_e32 v57, 16, v57
	v_mul_f32_e32 v20, v21, v19
	v_sub_f32_e32 v32, 1.0, v32
	v_mul_f32_e32 v23, v22, v18
	v_mul_f32_e32 v18, v17, v18
	v_min_f32_e32 v20, 0x5affcb9e, v20
	v_min_f32_e32 v18, 1.0, v18
	v_mul_f32_e32 v19, v19, v57
	v_min_f32_e32 v23, 0x5affcb9e, v23
	v_mul_f32_e32 v20, v20, v57
	v_cvt_pk_bf16_f32 v19, v19, v20
	v_mul_f32_e32 v18, v32, v18
	v_mul_f32_e32 v20, v32, v23
	v_cvt_pk_bf16_f32 v18, v20, v18
	ds_write_b16 v181, v19
	ds_write_b16_d16_hi v181, v19 offset:9216
	ds_write_b16 v181, v18 offset:18432
	v_add_f32_e32 v19, v30, v16
	v_exp_f32_e32 v20, v19
	v_min_f32_e64 v19, -v19, s33
	v_exp_f32_e32 v19, v19
	v_lshlrev_b32_e32 v55, 16, v55
	v_mul_f32_e32 v23, v21, v20
	v_sub_f32_e32 v33, 1.0, v33
	v_mul_f32_e32 v30, v22, v19
	v_mul_f32_e32 v19, v17, v19
	v_min_f32_e32 v23, 0x5affcb9e, v23
	v_min_f32_e32 v19, 1.0, v19
	v_mul_f32_e32 v20, v20, v55
	v_min_f32_e32 v30, 0x5affcb9e, v30
; #define GAS __attribute__((address_space(1)))
; __device__ __forceinline__ void hgrn_phase(const Params& p, int e, char* lds) {
;     ...
;         for (int i = 0; i < 8; ++i) { const float cc = off + cl[i];
;           const float e1 = __builtin_amdgcn_exp2f(cc), inv1 = __builtin_amdgcn_exp2f(fminf(-cc, 120.f));
;           const float ea = fminf(e1 * em, 3.6e16f), eb = fminf(inv1 * emi, 3.6e16f), es = fminf(inv1 * el, 1.0f);
;           const int t = 8 * rq + i;
;           const unsigned w0 = cvtpk(qf[i] * e1, qf[i] * ea), w1 = cvtpk(kk[i] * eb, kk[i] * es);
;           *(unsigned short*)(QD + t * PK + k * 2) = (unsigned short)(w0 & 0xffffu);
;           *(unsigned short*)(QA + t * PK + k * 2) = (unsigned short)(w0 >> 16);
;           *(unsigned short*)(KB + t * PK + k * 2) = (unsigned short)(w1 & 0xffffu);
;           if (i & 1) ksw[i >> 1] |= (w1 & 0xffff0000u); else ksw[i >> 1] = (w1 >> 16); }
;         *(u32x4*)(KS + k * PJ + rq * 16) = (u32x4){ksw[0], ksw[1], ksw[2], ksw[3]};
;         *(u32x4*)(VT + vv * PJ + jg * 32) = vpa; *(u32x4*)(VT + vv * PJ + jg * 32 + 16) = vpb; }
;       LBAR();
;       if (c + 1 < SEQ / 64) { const int bc = base0 + rsb * 64 * (c + 1); const int o0 = bc + rsb * lr;
;         gq = *(const GAS u32x4*)(bigc + (size_t)(unsigned)(o0 + qcol)); gz = *(const GAS u32x4*)(bigc + (size_t)(unsigned)(o0 + zcol));
;         gv0 = *(const GAS u32x4*)(bigc + (size_t)(unsigned)(bc + rsb * vr + vcol)); gv1 = *(const GAS u32x4*)(bigc + (size_t)(unsigned)(bc + rsb * (vr + 32) + vcol)); }
;     ...
;       f32x4 oacc[4];
;       const int wq = wave >> 1, vt0 = 4 * (wave & 1);
;       { const int ttA = 2 * (wave & 1); const char* STp = ST + pb * (128 * PK);
;         bf16x8 fa[2], fb0[2], fb1[2], fqd[2], fs[4][2];
; #pragma unroll
;         for (int ks = 0; ks < 2; ++ks) { fa[ks] = ldfrag(KB, 16 * wq + fr, PK, ks * 32 + fq_ * 8); fb0[ks] = ldfrag(QA, 16 * ttA + fr, PK, ks * 32 + fq_ * 8); fb1[ks] = ldfrag(QA, 16 * (ttA + 1) + fr, PK, ks * 32 + fq_ * 8);
;           fqd[ks] = ldfrag(QD, 16 * wq + fr, PK, ks * 32 + fq_ * 8);
; #pragma unroll
;           for (int n = 0; n < 4; ++n) fs[n][ks] = ldfrag(STp, 16 * (vt0 + n) + fr, PK, ks * 32 + fq_ * 8); }
;         HWAIT();
;         f32x4 acc0 = (f32x4){0.f, 0.f, 0.f, 0.f}, acc1 = acc0;
; #pragma unroll
;         for (int n = 0; n < 4; ++n) oacc[n] = acc0;
; #pragma unroll
;         for (int ks = 0; ks < 2; ++ks) {
	v_mul_f32_e32 v23, v23, v55
	v_cvt_pk_bf16_f32 v20, v20, v23
	v_mul_f32_e32 v19, v33, v19
	v_mul_f32_e32 v23, v33, v30
	v_cvt_pk_bf16_f32 v19, v23, v19
	ds_write_b16 v181, v20 offset:144
	ds_write_b16_d16_hi v181, v20 offset:9360
	ds_write_b16 v181, v19 offset:18576
	v_add_f32_e32 v20, v29, v16
	v_exp_f32_e32 v23, v20
	v_min_f32_e64 v20, -v20, s33
	v_exp_f32_e32 v20, v20
	v_lshrrev_b32_e32 v18, 16, v18
	v_and_or_b32 v18, v19, s13, v18
	v_mul_f32_e32 v19, v21, v23
	v_lshlrev_b32_e32 v54, 16, v54
	v_min_f32_e32 v19, 0x5affcb9e, v19
	v_mul_f32_e32 v29, v22, v20
	v_mul_f32_e32 v20, v17, v20
	v_sub_f32_e32 v34, 1.0, v34
	v_min_f32_e32 v20, 1.0, v20
	v_mul_f32_e32 v19, v19, v54
	v_min_f32_e32 v29, 0x5affcb9e, v29
	v_mul_f32_e32 v23, v23, v54
	v_cvt_pk_bf16_f32 v19, v23, v19
	v_mul_f32_e32 v20, v34, v20
	v_mul_f32_e32 v23, v34, v29
	v_cvt_pk_bf16_f32 v20, v23, v20
	ds_write_b16 v181, v19 offset:288
	ds_write_b16_d16_hi v181, v19 offset:9504
	ds_write_b16 v181, v20 offset:18720
	v_add_f32_e32 v19, v27, v16
	v_exp_f32_e32 v23, v19
	v_min_f32_e64 v19, -v19, s33
	v_exp_f32_e32 v19, v19
	v_lshlrev_b32_e32 v52, 16, v52
	v_mul_f32_e32 v27, v21, v23
	v_sub_f32_e32 v37, 1.0, v37
	v_mul_f32_e32 v29, v22, v19
	v_mul_f32_e32 v19, v17, v19
	v_min_f32_e32 v27, 0x5affcb9e, v27
	v_min_f32_e32 v19, 1.0, v19
	v_mul_f32_e32 v23, v23, v52
	v_min_f32_e32 v29, 0x5affcb9e, v29
	v_mul_f32_e32 v27, v27, v52
	v_cvt_pk_bf16_f32 v23, v23, v27
	v_mul_f32_e32 v19, v37, v19
	v_mul_f32_e32 v27, v37, v29
	v_cvt_pk_bf16_f32 v19, v27, v19
	ds_write_b16 v181, v23 offset:432
	ds_write_b16_d16_hi v181, v23 offset:9648
	ds_write_b16 v181, v19 offset:18864
	v_add_f32_e32 v23, v28, v16
	v_exp_f32_e32 v27, v23
	v_min_f32_e64 v23, -v23, s33
	v_exp_f32_e32 v23, v23
	v_lshrrev_b32_e32 v20, 16, v20
	v_and_or_b32 v19, v19, s13, v20
	v_mul_f32_e32 v20, v21, v27
	v_lshlrev_b32_e32 v50, 16, v50
	v_min_f32_e32 v20, 0x5affcb9e, v20
	v_mul_f32_e32 v28, v22, v23
	v_mul_f32_e32 v23, v17, v23
	v_sub_f32_e32 v65, 1.0, v38
	v_min_f32_e32 v23, 1.0, v23
	v_mul_f32_e32 v20, v20, v50
	v_min_f32_e32 v28, 0x5affcb9e, v28
	v_mul_f32_e32 v27, v27, v50
	v_cvt_pk_bf16_f32 v20, v27, v20
	v_mul_f32_e32 v23, v65, v23
	v_mul_f32_e32 v27, v65, v28
	v_cvt_pk_bf16_f32 v23, v27, v23
	ds_write_b16 v182, v20 offset:576
	ds_write_b16_d16_hi v182, v20 offset:9792
	ds_write_b16 v182, v23 offset:19008
	v_add_f32_e32 v20, v26, v16
	v_exp_f32_e32 v26, v20
	v_min_f32_e64 v20, -v20, s33
	v_exp_f32_e32 v20, v20
	v_lshlrev_b32_e32 v49, 16, v49
	v_mul_f32_e32 v27, v21, v26
	v_sub_f32_e32 v66, 1.0, v39
	v_mul_f32_e32 v28, v22, v20
	v_mul_f32_e32 v20, v17, v20
	v_min_f32_e32 v27, 0x5affcb9e, v27
	v_min_f32_e32 v20, 1.0, v20
	v_mul_f32_e32 v26, v26, v49
	v_min_f32_e32 v28, 0x5affcb9e, v28
	v_mul_f32_e32 v27, v27, v49
	v_cvt_pk_bf16_f32 v26, v26, v27
	v_mul_f32_e32 v20, v66, v20
	v_add_f32_e32 v25, v25, v16
	v_mul_f32_e32 v27, v66, v28
	v_cvt_pk_bf16_f32 v20, v27, v20
	ds_write_b16 v182, v26 offset:720
	ds_write_b16_d16_hi v182, v26 offset:9936
	ds_write_b16 v182, v20 offset:19152
	v_exp_f32_e32 v26, v25
	v_min_f32_e64 v25, -v25, s33
	v_exp_f32_e32 v25, v25
	v_lshrrev_b32_e32 v23, 16, v23
	v_and_or_b32 v20, v20, s13, v23
	v_mul_f32_e32 v23, v21, v26
	v_lshlrev_b32_e32 v67, 16, v47
	v_min_f32_e32 v23, 0x5affcb9e, v23
	v_mul_f32_e32 v27, v22, v25
	v_mul_f32_e32 v25, v17, v25
	v_sub_f32_e32 v68, 1.0, v40
	v_min_f32_e32 v25, 1.0, v25
	v_mul_f32_e32 v23, v23, v67
	v_min_f32_e32 v27, 0x5affcb9e, v27
	v_mul_f32_e32 v26, v26, v67
	v_cvt_pk_bf16_f32 v23, v26, v23
	v_mul_f32_e32 v25, v68, v25
	v_add_f32_e32 v16, v24, v16
	v_mul_f32_e32 v26, v68, v27
	v_cvt_pk_bf16_f32 v25, v26, v25
	ds_write_b16 v182, v23 offset:864
	ds_write_b16_d16_hi v182, v23 offset:10080
	ds_write_b16 v182, v25 offset:19296
	v_exp_f32_e32 v23, v16
	v_min_f32_e64 v16, -v16, s33
	v_exp_f32_e32 v16, v16
	v_lshlrev_b32_e32 v69, 16, v45
	v_mul_f32_e32 v21, v21, v23
	v_min_f32_e32 v21, 0x5affcb9e, v21
	v_mul_f32_e32 v22, v22, v16
	v_mul_f32_e32 v16, v17, v16
	v_sub_f32_e32 v70, 1.0, v41
	v_min_f32_e32 v22, 0x5affcb9e, v22
	v_min_f32_e32 v16, 1.0, v16
	v_mul_f32_e32 v17, v23, v69
	v_mul_f32_e32 v21, v21, v69
	v_lshrrev_b32_e32 v24, 16, v25
	v_cvt_pk_bf16_f32 v17, v17, v21
	v_mul_f32_e32 v21, v70, v22
	v_mul_f32_e32 v16, v70, v16
	v_cvt_pk_bf16_f32 v16, v21, v16
	v_perm_b32 v41, v64, v63, s7
	v_and_or_b32 v21, v16, s13, v24
	v_perm_b32 v40, v62, v61, s7
	v_perm_b32 v39, v60, v59, s7
	v_perm_b32 v38, v58, v56, s7
	v_perm_b32 v47, v53, v51, s7
	v_perm_b32 v46, v48, v46, s7
	v_perm_b32 v45, v44, v43, s7
	v_perm_b32 v44, v36, v35, s7
	ds_write_b16 v182, v17 offset:1008
	ds_write_b16_d16_hi v182, v17 offset:10224
	ds_write_b16 v182, v16 offset:19440
	ds_write_b128 v154, v[18:21] offset:27648
	ds_write_b128 v155, v[44:47] offset:36864
	ds_write_b128 v183, v[38:41] offset:36880
	s_waitcnt lgkmcnt(0)
	s_barrier
	v_add_u32_e32 v16, s8, v172
	v_add_u32_e32 v20, v171, v170
	v_add_u32_e32 v24, vcc_hi, v169
	v_add_u32_e32 v28, vcc_hi, v168
	global_load_dwordx4 v[16:19], v16, s[30:31]
	s_nop 0
	global_load_dwordx4 v[20:23], v20, s[30:31]
	s_nop 0
	global_load_dwordx4 v[24:27], v24, s[30:31]
	s_nop 0
	global_load_dwordx4 v[28:31], v28, s[30:31]
	s_and_b32 s14, vcc_lo, 1
	s_mul_i32 s5, s14, 0x4800
	v_add_u32_e32 v32, s5, v122
	v_add_u32_e32 v36, v32, v101
	v_add_u32_e32 v37, v32, v119
	v_add_u32_e32 v38, v32, v120
	v_add_u32_e32 v39, v32, v121
	v_add_u32_e32 v173, v111, v110
	ds_read_b128 v[76:79], v156 offset:18432
	ds_read_b128 v[56:59], v156 offset:18496
	ds_read_b128 v[52:55], v173 offset:9216
	ds_read_b128 v[68:71], v173 offset:9280
	ds_read_b128 v[84:87], v173 offset:11520
	ds_read_b128 v[64:67], v173 offset:11584
	ds_read_b128 v[72:75], v156
	ds_read_b128 v[32:35], v156 offset:64
	ds_read_b128 v[80:83], v36 offset:64512
	ds_read_b128 v[48:51], v36 offset:64576
	ds_read_b128 v[88:91], v37 offset:64512
	ds_read_b128 v[44:47], v37 offset:64576
	ds_read_b128 v[92:95], v38 offset:64512
	ds_read_b128 v[40:43], v38 offset:64576
	ds_read_b128 v[96:99], v39 offset:64512
	ds_read_b128 v[36:39], v39 offset:64576
	v_mov_b32_e32 v145, v144
	v_mov_b32_e32 v146, v144
	v_mov_b32_e32 v147, v144
	v_mov_b64_e32 v[60:61], v[144:145]
	v_mov_b64_e32 v[62:63], v[146:147]
	s_and_saveexec_b64 s[26:27], s[44:45]
	s_cbranch_execz .LBB0_226
	s_waitcnt lgkmcnt(13)
	v_mfma_f32_16x16x32_bf16 v[60:63], v[76:79], v[52:55], 0

; __device__ __forceinline__ void hgrn_phase(const Params& p, int e, char* lds) {
;     ...
;       *(u32x4*)(RQ + lr * PK + lc8 * 2) = gq; *(u32x4*)(RZ + lr * PK + lc8 * 2) = gz;
;       *(u32x4*)(RV + vr * PV + vc8 * 2) = gv0; *(u32x4*)(RV + (vr + 32) * PV + vc8 * 2) = gv1;
;       LBAR();
;       float qf[8], kk[8], cl[8]; float run = 0.f;
; #pragma unroll
;       for (int i = 0; i < 8; ++i) { const int t = 8 * rq + i; const float z = bf2f(*(const unsigned short*)(RZ + t * PK + k * 2)); qf[i] = bf2f(*(const unsigned short*)(RQ + t * PK + k * 2));
;         const float sg = __builtin_amdgcn_rcpf(1.0f + __builtin_amdgcn_exp2f(-L2E * z)); const float f = lbk + (1.0f - lbk) * sg;
;         run += __builtin_amdgcn_logf(f); cl[i] = run; kk[i] = 1.0f - f; }
;       TOT[rq * 64 + k] = run;
;       unsigned short rvv[16];
; #pragma unroll
;       for (int i = 0; i < 16; ++i) rvv[i] = *(const unsigned short*)(RV + (16 * jg + i) * PV + vv * 2);
;       u32x4 vpa, vpb;
;       vpa.x = rvv[0] | ((unsigned)rvv[1] << 16); vpa.y = rvv[2] | ((unsigned)rvv[3] << 16); vpa.z = rvv[4] | ((unsigned)rvv[5] << 16); vpa.w = rvv[6] | ((unsigned)rvv[7] << 16);
;       vpb.x = rvv[8] | ((unsigned)rvv[9] << 16); vpb.y = rvv[10] | ((unsigned)rvv[11] << 16); vpb.z = rvv[12] | ((unsigned)rvv[13] << 16); vpb.w = rvv[14] | ((unsigned)rvv[15] << 16);
;       LBAR();
;       { float tt[8];
; #pragma unroll
;         for (int r8 = 0; r8 < 8; ++r8) tt[r8] = TOT[r8 * 64 + k];
;         const float mid = (tt[0] + tt[1]) + (tt[2] + tt[3]), last = mid + ((tt[4] + tt[5]) + (tt[6] + tt[7]));
;         float off = 0.f;
; #pragma unroll
;         for (int r8 = 0; r8 < 7; ++r8) off += (r8 < rq) ? tt[r8] : 0.f;
;         const float el = __builtin_amdgcn_exp2f(last), em = __builtin_amdgcn_exp2f(fminf(-mid, 120.f)), emi = __builtin_amdgcn_exp2f(mid);
;         if (rq == 0) DD[k] = el;
;         unsigned ksw[4];
; #pragma unroll
;         for (int i = 0; i < 8; ++i) { const float cc = off + cl[i];
;           const float e1 = __builtin_amdgcn_exp2f(cc), inv1 = __builtin_amdgcn_exp2f(fminf(-cc, 120.f));
;           const float ea = fminf(e1 * em, 3.6e16f), eb = fminf(inv1 * emi, 3.6e16f), es = fminf(inv1 * el, 1.0f);
;           const int t = 8 * rq + i;
;           const unsigned w0 = cvtpk(qf[i] * e1, qf[i] * ea), w1 = cvtpk(kk[i] * eb, kk[i] * es);
.LBB0_232:
	s_waitcnt vmcnt(19)
	ds_write_b128 v143, v[16:19]
	s_waitcnt vmcnt(18)
	ds_write_b128 v143, v[20:23] offset:9216
	s_waitcnt vmcnt(17)
	ds_write_b128 v152, v[24:27] offset:18432
	s_waitcnt vmcnt(16)
	ds_write_b128 v152, v[28:31] offset:27136
	s_waitcnt lgkmcnt(0)
	s_barrier
	ds_read_u16 v16, v100 offset:9216
	ds_read_u16 v17, v100 offset:9360
	ds_read_u16 v18, v100 offset:9504
	ds_read_u16 v19, v100 offset:9648
	ds_read_u16 v20, v100 offset:9792
	ds_read_u16 v21, v100 offset:9936
	ds_read_u16 v22, v100 offset:10080
	ds_read_u16 v23, v100 offset:10224
	s_waitcnt lgkmcnt(6)
	v_lshlrev_b32_e32 v17, 16, v17
	v_mul_f32_e32 v17, 0xbfb8aa3b, v17
	v_exp_f32_e32 v17, v17
	v_lshlrev_b32_e32 v16, 16, v16
	v_mul_f32_e32 v16, 0xbfb8aa3b, v16
	s_waitcnt lgkmcnt(5)
	v_lshlrev_b32_e32 v18, 16, v18
	v_exp_f32_e32 v16, v16
	v_add_f32_e32 v17, 1.0, v17
	v_mul_f32_e32 v18, 0xbfb8aa3b, v18
	v_rcp_f32_e32 v17, v17
	v_exp_f32_e32 v18, v18
	v_add_f32_e32 v16, 1.0, v16
	v_rcp_f32_e32 v16, v16
	v_fma_f32 v33, v163, v17, v162
	v_add_f32_e32 v17, 1.0, v18
	s_waitcnt lgkmcnt(4)
	v_lshlrev_b32_e32 v18, 16, v19
	v_mul_f32_e32 v18, 0xbfb8aa3b, v18
	v_rcp_f32_e32 v17, v17
	v_exp_f32_e32 v18, v18
	v_fma_f32 v32, v163, v16, v162
	v_log_f32_e32 v16, v32
	v_log_f32_e32 v19, v33
	v_fma_f32 v34, v163, v17, v162
	v_add_f32_e32 v18, 1.0, v18
	v_log_f32_e32 v17, v34
	v_rcp_f32_e32 v18, v18
	v_add_f32_e32 v31, 0, v16
	v_add_f32_e32 v30, v31, v19
	v_add_f32_e32 v29, v30, v17
	v_fma_f32 v36, v163, v18, v162
	s_waitcnt lgkmcnt(3)
	v_lshlrev_b32_e32 v17, 16, v20
	s_waitcnt lgkmcnt(2)
	v_lshlrev_b32_e32 v18, 16, v21
	v_mul_f32_e32 v17, 0xbfb8aa3b, v17
	v_mul_f32_e32 v18, 0xbfb8aa3b, v18
	v_log_f32_e32 v16, v36
	v_exp_f32_e32 v17, v17
	v_exp_f32_e32 v18, v18
	ds_read_u16 v56, v100
	ds_read_u16 v54, v100 offset:144
	ds_read_u16 v53, v100 offset:288
	ds_read_u16 v51, v100 offset:432
	ds_read_u16 v49, v100 offset:576
	ds_read_u16 v48, v100 offset:720
	ds_read_u16 v46, v100 offset:864
	ds_read_u16 v44, v100 offset:1008
	v_add_f32_e32 v27, v29, v16
	v_add_f32_e32 v16, 1.0, v17
	v_add_f32_e32 v17, 1.0, v18
	s_waitcnt lgkmcnt(9)
	v_lshlrev_b32_e32 v18, 16, v22
	v_mul_f32_e32 v18, 0xbfb8aa3b, v18
	v_rcp_f32_e32 v17, v17
	v_exp_f32_e32 v18, v18
	v_rcp_f32_e32 v16, v16
	v_fma_f32 v39, v163, v17, v162
	v_add_f32_e32 v17, 1.0, v18
	s_waitcnt lgkmcnt(8)
	v_lshlrev_b32_e32 v18, 16, v23
	v_mul_f32_e32 v18, 0xbfb8aa3b, v18
	v_exp_f32_e32 v18, v18
	v_rcp_f32_e32 v17, v17
	v_fma_f32 v38, v163, v16, v162
	v_log_f32_e32 v16, v38
	v_add_f32_e32 v18, 1.0, v18
	v_rcp_f32_e32 v18, v18
	v_log_f32_e32 v19, v39
	v_fma_f32 v40, v163, v17, v162
	v_log_f32_e32 v17, v40
	v_fmac_f32_e32 v162, v163, v18
	v_add_f32_e32 v28, v27, v16
	v_log_f32_e32 v16, v162
	v_add_f32_e32 v26, v28, v19
	v_add_f32_e32 v25, v26, v17
	v_add_f32_e32 v24, v25, v16
	ds_write_b32 v107, v24
	ds_read_u16 v35, v153 offset:18432
	ds_read_u16 v37, v153 offset:18704
	ds_read_u16 v41, v153 offset:18976
	ds_read_u16 v43, v153 offset:19248
	ds_read_u16 v45, v153 offset:19520
	ds_read_u16 v47, v153 offset:19792
	ds_read_u16 v50, v153 offset:20064
	ds_read_u16 v52, v153 offset:20336
	ds_read_u16 v55, v153 offset:20608
	ds_read_u16 v57, v153 offset:20880
	ds_read_u16 v58, v153 offset:21152
	ds_read_u16 v59, v153 offset:21424
	ds_read_u16 v60, v153 offset:21696
	ds_read_u16 v61, v153 offset:21968
	ds_read_u16 v62, v153 offset:22240
	ds_read_u16 v63, v153 offset:22512
	s_waitcnt lgkmcnt(0)
	s_barrier
	ds_read2st64_b32 v[20:21], v108 offset0:2 offset1:3
	ds_read2st64_b32 v[18:19], v108 offset0:4 offset1:5
	ds_read2st64_b32 v[16:17], v108 offset0:6 offset1:7
	ds_read2st64_b32 v[22:23], v108 offset1:1
	s_waitcnt lgkmcnt(3)
	v_add_f32_e32 v42, v20, v21
	s_waitcnt lgkmcnt(2)
	v_add_f32_e32 v64, v18, v19
	s_waitcnt lgkmcnt(1)
	v_add_f32_e32 v17, v16, v17
	v_add_f32_e32 v17, v64, v17
	s_waitcnt lgkmcnt(0)
	v_add_f32_e32 v64, v22, v23
	v_add_f32_e32 v42, v64, v42
	v_add_f32_e32 v17, v42, v17
	v_exp_f32_e32 v17, v17
	s_and_saveexec_b64 s[26:27], s[42:43]
	ds_write_b32 v109, v17
	s_or_b64 exec, exec, s[26:27]
	v_add_f32_e32 v22, 0, v22
	v_cndmask_b32_e64 v22, 0, v22, s[64:65]
	v_cndmask_b32_e64 v23, 0, v23, s[66:67]
	v_add_f32_e32 v22, v22, v23
	v_cndmask_b32_e64 v20, 0, v20, s[68:69]
	v_add_f32_e32 v20, v22, v20
	v_cndmask_b32_e64 v21, 0, v21, s[70:71]
	v_add_f32_e32 v20, v20, v21
	v_cndmask_b32_e64 v18, 0, v18, s[72:73]
	v_add_f32_e32 v18, v20, v18
	v_cndmask_b32_e64 v19, 0, v19, s[74:75]
	v_add_f32_e32 v18, v18, v19
	v_cndmask_b32_e64 v16, 0, v16, s[76:77]
	v_add_f32_e32 v16, v18, v16
	v_max_f32_e64 v18, -v42, -v42
	v_min_f32_e32 v18, 0x42f00000, v18
	v_exp_f32_e32 v21, v18
	v_add_f32_e32 v18, v31, v16
	v_exp_f32_e32 v19, v18
	v_min_f32_e64 v18, -v18, s33
	v_exp_f32_e32 v22, v42
	v_exp_f32_e32 v18, v18
	v_lshlrev_b32_e32 v56, 16, v56
	v_mul_f32_e32 v20, v21, v19
	v_sub_f32_e32 v32, 1.0, v32
	v_mul_f32_e32 v23, v22, v18
	v_mul_f32_e32 v18, v17, v18
	v_min_f32_e32 v20, 0x5affcb9e, v20
	v_min_f32_e32 v18, 1.0, v18
	v_mul_f32_e32 v19, v19, v56
	v_min_f32_e32 v23, 0x5affcb9e, v23
	v_mul_f32_e32 v20, v20, v56
	v_cvt_pk_bf16_f32 v19, v19, v20
	v_mul_f32_e32 v18, v32, v18
	v_mul_f32_e32 v20, v32, v23
	v_cvt_pk_bf16_f32 v18, v20, v18
	ds_write_b16 v181, v19
	ds_write_b16_d16_hi v181, v19 offset:9216
	ds_write_b16 v181, v18 offset:18432
	v_add_f32_e32 v19, v30, v16
	v_exp_f32_e32 v20, v19
	v_min_f32_e64 v19, -v19, s33
	v_exp_f32_e32 v19, v19
	v_lshlrev_b32_e32 v54, 16, v54
	v_mul_f32_e32 v23, v21, v20
	v_sub_f32_e32 v33, 1.0, v33
	v_mul_f32_e32 v30, v22, v19
	v_mul_f32_e32 v19, v17, v19
	v_min_f32_e32 v23, 0x5affcb9e, v23
	v_min_f32_e32 v19, 1.0, v19
; #define GAS __attribute__((address_space(1)))
; __device__ __forceinline__ void hgrn_phase(const Params& p, int e, char* lds) {
;     ...
;         for (int i = 0; i < 8; ++i) { const float cc = off + cl[i];
;           const float e1 = __builtin_amdgcn_exp2f(cc), inv1 = __builtin_amdgcn_exp2f(fminf(-cc, 120.f));
;           const float ea = fminf(e1 * em, 3.6e16f), eb = fminf(inv1 * emi, 3.6e16f), es = fminf(inv1 * el, 1.0f);
;           const int t = 8 * rq + i;
;           const unsigned w0 = cvtpk(qf[i] * e1, qf[i] * ea), w1 = cvtpk(kk[i] * eb, kk[i] * es);
;           *(unsigned short*)(QD + t * PK + k * 2) = (unsigned short)(w0 & 0xffffu);
;           *(unsigned short*)(QA + t * PK + k * 2) = (unsigned short)(w0 >> 16);
;           *(unsigned short*)(KB + t * PK + k * 2) = (unsigned short)(w1 & 0xffffu);
;           if (i & 1) ksw[i >> 1] |= (w1 & 0xffff0000u); else ksw[i >> 1] = (w1 >> 16); }
;         *(u32x4*)(KS + k * PJ + rq * 16) = (u32x4){ksw[0], ksw[1], ksw[2], ksw[3]};
;         *(u32x4*)(VT + vv * PJ + jg * 32) = vpa; *(u32x4*)(VT + vv * PJ + jg * 32 + 16) = vpb; }
;       LBAR();
;       if (c + 1 < SEQ / 64) { const int bc = base0 + rsb * 64 * (c + 1); const int o0 = bc + rsb * lr;
;         gq = *(const GAS u32x4*)(bigc + (size_t)(unsigned)(o0 + qcol)); gz = *(const GAS u32x4*)(bigc + (size_t)(unsigned)(o0 + zcol));
;         gv0 = *(const GAS u32x4*)(bigc + (size_t)(unsigned)(bc + rsb * vr + vcol)); gv1 = *(const GAS u32x4*)(bigc + (size_t)(unsigned)(bc + rsb * (vr + 32) + vcol)); }
;     ...
;       f32x4 oacc[4];
;       const int wq = wave >> 1, vt0 = 4 * (wave & 1);
;       { const int ttA = 2 * (wave & 1); const char* STp = ST + pb * (128 * PK);
;         bf16x8 fa[2], fb0[2], fb1[2], fqd[2], fs[4][2];
; #pragma unroll
;         for (int ks = 0; ks < 2; ++ks) { fa[ks] = ldfrag(KB, 16 * wq + fr, PK, ks * 32 + fq_ * 8); fb0[ks] = ldfrag(QA, 16 * ttA + fr, PK, ks * 32 + fq_ * 8); fb1[ks] = ldfrag(QA, 16 * (ttA + 1) + fr, PK, ks * 32 + fq_ * 8);
;           fqd[ks] = ldfrag(QD, 16 * wq + fr, PK, ks * 32 + fq_ * 8);
; #pragma unroll
;           for (int n = 0; n < 4; ++n) fs[n][ks] = ldfrag(STp, 16 * (vt0 + n) + fr, PK, ks * 32 + fq_ * 8); }
;         HWAIT();
;         f32x4 acc0 = (f32x4){0.f, 0.f, 0.f, 0.f}, acc1 = acc0;
; #pragma unroll
;         for (int n = 0; n < 4; ++n) oacc[n] = acc0;
; #pragma unroll
;         for (int ks = 0; ks < 2; ++ks) {
	v_mul_f32_e32 v20, v20, v54
	v_min_f32_e32 v30, 0x5affcb9e, v30
	v_mul_f32_e32 v23, v23, v54
	v_cvt_pk_bf16_f32 v20, v20, v23
	v_mul_f32_e32 v19, v33, v19
	v_mul_f32_e32 v23, v33, v30
	v_cvt_pk_bf16_f32 v19, v23, v19
	ds_write_b16 v181, v20 offset:144
	ds_write_b16_d16_hi v181, v20 offset:9360
	ds_write_b16 v181, v19 offset:18576
	v_add_f32_e32 v20, v29, v16
	v_exp_f32_e32 v23, v20
	v_min_f32_e64 v20, -v20, s33
	v_exp_f32_e32 v20, v20
	v_lshrrev_b32_e32 v18, 16, v18
	v_and_or_b32 v18, v19, s13, v18
	v_mul_f32_e32 v19, v21, v23
	v_lshlrev_b32_e32 v53, 16, v53
	v_min_f32_e32 v19, 0x5affcb9e, v19
	v_mul_f32_e32 v29, v22, v20
	v_mul_f32_e32 v20, v17, v20
	v_sub_f32_e32 v34, 1.0, v34
	v_min_f32_e32 v20, 1.0, v20
	v_mul_f32_e32 v19, v19, v53
	v_min_f32_e32 v29, 0x5affcb9e, v29
	v_mul_f32_e32 v23, v23, v53
	v_cvt_pk_bf16_f32 v19, v23, v19
	v_mul_f32_e32 v20, v34, v20
	v_mul_f32_e32 v23, v34, v29
	v_cvt_pk_bf16_f32 v20, v23, v20
	ds_write_b16 v181, v19 offset:288
	ds_write_b16_d16_hi v181, v19 offset:9504
	ds_write_b16 v181, v20 offset:18720
	v_add_f32_e32 v19, v27, v16
	v_exp_f32_e32 v23, v19
	v_min_f32_e64 v19, -v19, s33
	v_exp_f32_e32 v19, v19
	v_lshlrev_b32_e32 v51, 16, v51
	v_mul_f32_e32 v27, v21, v23
	v_sub_f32_e32 v36, 1.0, v36
	v_mul_f32_e32 v29, v22, v19
	v_mul_f32_e32 v19, v17, v19
	v_min_f32_e32 v27, 0x5affcb9e, v27
	v_min_f32_e32 v19, 1.0, v19
	v_mul_f32_e32 v23, v23, v51
	v_min_f32_e32 v29, 0x5affcb9e, v29
	v_mul_f32_e32 v27, v27, v51
	v_cvt_pk_bf16_f32 v23, v23, v27
	v_mul_f32_e32 v19, v36, v19
	v_mul_f32_e32 v27, v36, v29
	v_cvt_pk_bf16_f32 v19, v27, v19
	ds_write_b16 v181, v23 offset:432
	ds_write_b16_d16_hi v181, v23 offset:9648
	ds_write_b16 v181, v19 offset:18864
	v_add_f32_e32 v23, v28, v16
	v_exp_f32_e32 v27, v23
	v_min_f32_e64 v23, -v23, s33
	v_exp_f32_e32 v23, v23
	v_lshrrev_b32_e32 v20, 16, v20
	v_and_or_b32 v19, v19, s13, v20
	v_mul_f32_e32 v20, v21, v27
	v_lshlrev_b32_e32 v64, 16, v49
	v_min_f32_e32 v20, 0x5affcb9e, v20
	v_mul_f32_e32 v28, v22, v23
	v_mul_f32_e32 v23, v17, v23
	v_sub_f32_e32 v38, 1.0, v38
	v_min_f32_e32 v23, 1.0, v23
	v_mul_f32_e32 v20, v20, v64
	v_min_f32_e32 v28, 0x5affcb9e, v28
	v_mul_f32_e32 v27, v27, v64
	v_cvt_pk_bf16_f32 v20, v27, v20
	v_mul_f32_e32 v23, v38, v23
	v_mul_f32_e32 v27, v38, v28
	v_cvt_pk_bf16_f32 v23, v27, v23
	ds_write_b16 v182, v20 offset:576
	ds_write_b16_d16_hi v182, v20 offset:9792
	ds_write_b16 v182, v23 offset:19008
	v_add_f32_e32 v20, v26, v16
	v_exp_f32_e32 v26, v20
	v_min_f32_e64 v20, -v20, s33
	v_exp_f32_e32 v20, v20
	v_lshlrev_b32_e32 v65, 16, v48
	v_mul_f32_e32 v27, v21, v26
	v_sub_f32_e32 v39, 1.0, v39
	v_mul_f32_e32 v28, v22, v20
	v_mul_f32_e32 v20, v17, v20
	v_min_f32_e32 v27, 0x5affcb9e, v27
	v_min_f32_e32 v20, 1.0, v20
	v_mul_f32_e32 v26, v26, v65
	v_min_f32_e32 v28, 0x5affcb9e, v28
	v_mul_f32_e32 v27, v27, v65
	v_cvt_pk_bf16_f32 v26, v26, v27
	v_mul_f32_e32 v20, v39, v20
	v_add_f32_e32 v25, v25, v16
	v_mul_f32_e32 v27, v39, v28
	v_cvt_pk_bf16_f32 v20, v27, v20
	ds_write_b16 v182, v26 offset:720
	ds_write_b16_d16_hi v182, v26 offset:9936
	ds_write_b16 v182, v20 offset:19152
	v_exp_f32_e32 v26, v25
	v_min_f32_e64 v25, -v25, s33
	v_exp_f32_e32 v25, v25
	v_lshrrev_b32_e32 v23, 16, v23
	v_and_or_b32 v20, v20, s13, v23
	v_mul_f32_e32 v23, v21, v26
	v_lshlrev_b32_e32 v66, 16, v46
	v_min_f32_e32 v23, 0x5affcb9e, v23
	v_mul_f32_e32 v27, v22, v25
	v_mul_f32_e32 v25, v17, v25
	v_sub_f32_e32 v40, 1.0, v40
	v_min_f32_e32 v25, 1.0, v25
	v_mul_f32_e32 v23, v23, v66
	v_min_f32_e32 v27, 0x5affcb9e, v27
	v_mul_f32_e32 v26, v26, v66
	v_cvt_pk_bf16_f32 v23, v26, v23
	v_mul_f32_e32 v25, v40, v25
	v_add_f32_e32 v16, v24, v16
	v_mul_f32_e32 v26, v40, v27
	v_cvt_pk_bf16_f32 v25, v26, v25
	ds_write_b16 v182, v23 offset:864
	ds_write_b16_d16_hi v182, v23 offset:10080
	ds_write_b16 v182, v25 offset:19296
	v_exp_f32_e32 v23, v16
	v_min_f32_e64 v16, -v16, s33
	v_exp_f32_e32 v16, v16
	v_lshlrev_b32_e32 v44, 16, v44
	v_mul_f32_e32 v21, v21, v23
	v_min_f32_e32 v21, 0x5affcb9e, v21
	v_mul_f32_e32 v22, v22, v16
	v_mul_f32_e32 v16, v17, v16
	v_sub_f32_e32 v67, 1.0, v162
	v_min_f32_e32 v22, 0x5affcb9e, v22
	v_min_f32_e32 v16, 1.0, v16
	v_mul_f32_e32 v17, v23, v44
	v_mul_f32_e32 v21, v21, v44
	v_lshrrev_b32_e32 v24, 16, v25
	v_cvt_pk_bf16_f32 v17, v17, v21
	v_mul_f32_e32 v21, v67, v22
	v_mul_f32_e32 v16, v67, v16
	v_cvt_pk_bf16_f32 v16, v21, v16
	v_perm_b32 v63, v63, v62, s7
	v_and_or_b32 v21, v16, s13, v24
	v_perm_b32 v62, v61, v60, s7
	v_perm_b32 v61, v59, v58, s7
	v_perm_b32 v60, v57, v55, s7
	v_perm_b32 v49, v52, v50, s7
	v_perm_b32 v48, v47, v45, s7
	v_perm_b32 v47, v43, v41, s7
	v_perm_b32 v46, v37, v35, s7
	ds_write_b16 v182, v17 offset:1008
	ds_write_b16_d16_hi v182, v17 offset:10224
	ds_write_b16 v182, v16 offset:19440
	ds_write_b128 v154, v[18:21] offset:27648
	ds_write_b128 v155, v[46:49] offset:36864
	ds_write_b128 v183, v[60:63] offset:36880
	s_waitcnt lgkmcnt(0)
	s_barrier
	v_add_u32_e32 v16, v127, v101
	v_add_u32_e32 v17, v127, v119
	ds_read_b128 v[56:59], v16
	ds_read_b128 v[60:63], v17
	v_add_u32_e32 v16, v127, v120
	v_add_u32_e32 v17, v127, v121
	ds_read_b128 v[64:67], v16
	ds_read_b128 v[68:71], v17
	ds_read_b128 v[72:75], v156 offset:18432
	ds_read_b128 v[44:47], v156 offset:18496
	ds_read_b128 v[24:27], v173 offset:9216
	ds_read_b128 v[52:55], v173 offset:9280
	ds_read_b128 v[80:83], v173 offset:11520
	ds_read_b128 v[48:51], v173 offset:11584
	ds_read_b128 v[76:79], v156
	ds_read_b128 v[16:19], v156 offset:64
	ds_read_b128 v[40:43], v139
	ds_read_b128 v[36:39], v140
	ds_read_b128 v[32:35], v141
	ds_read_b128 v[20:23], v142
	v_mov_b32_e32 v145, v144
	v_mov_b32_e32 v146, v144
	v_mov_b32_e32 v147, v144
	v_mov_b64_e32 v[28:29], v[144:145]
	v_mov_b64_e32 v[30:31], v[146:147]
	s_and_saveexec_b64 s[26:27], s[44:45]
	s_cbranch_execz .LBB0_236
	s_waitcnt lgkmcnt(9)
	v_mfma_f32_16x16x32_bf16 v[28:31], v[72:75], v[24:27], 0
